# GEMM loop: s_setprio 1 for the post-barrier half (fragment reads + DMA issue + MFMA batch 2), s_setprio 0 at loop head
# speedup vs baseline: 1.1117x; 1.0105x over previous
.Lg92_loop:
	s_setprio 0
	s_waitcnt lgkmcnt(0)
	v_mfma_f32_32x32x16_bf16 v[114:129], v[162:165], v[228:231], v[114:129]
	ds_read_b128 v[166:169], v136 offset:0
	ds_read_b128 v[232:235], v137 offset:0
	s_add_i32 s9, s9, 1
	s_add_i32 s14, s9, 2
	s_lshl_b64 s[12:13], s[14:15], 14
	s_add_u32 s12, s12, s74
	s_addc_u32 s13, s13, s75
	v_mfma_f32_32x32x16_bf16 v[98:113], v[162:165], v[236:239], v[98:113]
	ds_read_b128 v[240:243], v137 offset:2048
	ds_read_b128 v[208:211], v136 offset:2048
	v_mfma_f32_32x32x16_bf16 v[82:97], v[204:207], v[228:231], v[82:97]
	ds_read_b128 v[216:219], v136 offset:4096
	ds_read_b128 v[224:227], v136 offset:6144
	v_mfma_f32_32x32x16_bf16 v[66:81], v[204:207], v[236:239], v[66:81]
	v_mfma_f32_32x32x16_bf16 v[50:65], v[212:215], v[228:231], v[50:65]
	v_mfma_f32_32x32x16_bf16 v[34:49], v[212:215], v[236:239], v[34:49]
	v_mfma_f32_32x32x16_bf16 v[18:33], v[220:223], v[228:231], v[18:33]
	v_mfma_f32_32x32x16_bf16 v[2:17], v[220:223], v[236:239], v[2:17]
	s_waitcnt vmcnt(6) lgkmcnt(0)
	s_barrier
	s_setprio 1
	s_add_u32 m0, s34, s72
	s_mov_b32 s34, s73
	s_add_u32 s73, s34, 0x6000
	s_cmp_lt_u32 s73, 0x12000
	s_cselect_b32 s73, s73, 0
	v_mfma_f32_32x32x16_bf16 v[114:129], v[166:169], v[232:235], v[114:129]
	ds_read_b128 v[162:165], v138 offset:0
	ds_read_b128 v[228:231], v139 offset:0
	v_mfma_f32_32x32x16_bf16 v[98:113], v[166:169], v[240:243], v[98:113]
	ds_read_b128 v[236:239], v139 offset:2048
	ds_read_b128 v[204:207], v138 offset:2048
	v_add_u32_e32 v136, s34, v134
	v_add_u32_e32 v137, s34, v135
	v_mfma_f32_32x32x16_bf16 v[82:97], v[208:211], v[232:235], v[82:97]
	ds_read_b128 v[212:215], v138 offset:4096
	ds_read_b128 v[220:223], v138 offset:6144
	v_mfma_f32_32x32x16_bf16 v[66:81], v[208:211], v[240:243], v[66:81]
	global_load_lds_dwordx4 v140, s[12:13]
	s_add_u32 m0, m0, 0x1000
	s_add_u32 s12, s12, 0x1000
	s_addc_u32 s13, s13, 0
	v_add_u32_e32 v138, s73, v132
	v_add_u32_e32 v139, s73, v133
	v_mfma_f32_32x32x16_bf16 v[50:65], v[216:219], v[232:235], v[50:65]
	global_load_lds_dwordx4 v140, s[12:13]
	s_add_u32 m0, m0, 0x1000
	s_add_u32 s12, s12, 0x1000
	s_addc_u32 s13, s13, 0
	v_mfma_f32_32x32x16_bf16 v[34:49], v[216:219], v[240:243], v[34:49]
	global_load_lds_dwordx4 v140, s[12:13]
	s_add_u32 m0, m0, 0x1000
	s_add_u32 s12, s12, 0x1000
	s_addc_u32 s13, s13, 0
	v_mfma_f32_32x32x16_bf16 v[18:33], v[224:227], v[232:235], v[18:33]
	global_load_lds_dwordx4 v140, s[12:13]
	s_add_u32 m0, m0, 0x1000
	s_lshl_b64 s[12:13], s[14:15], 13
	s_add_u32 s12, s12, s76
	s_addc_u32 s13, s13, s77
	v_mfma_f32_32x32x16_bf16 v[2:17], v[224:227], v[240:243], v[2:17]
	global_load_lds_dwordx4 v140, s[12:13]
	s_add_u32 m0, m0, 0x1000
	s_add_u32 s12, s12, 0x1000
	s_addc_u32 s13, s13, 0
	s_nop 0
	global_load_lds_dwordx4 v140, s[12:13]
	s_cmp_lg_u32 s9, 29
	s_cbranch_scc1 .Lg92_loop
	s_setprio 0
	s_waitcnt lgkmcnt(0)
	v_mfma_f32_32x32x16_bf16 v[114:129], v[162:165], v[228:231], v[114:129]
	ds_read_b128 v[166:169], v136 offset:0
	ds_read_b128 v[232:235], v137 offset:0
	s_add_i32 s9, s9, 1
	v_mfma_f32_32x32x16_bf16 v[98:113], v[162:165], v[236:239], v[98:113]
	ds_read_b128 v[240:243], v137 offset:2048
	ds_read_b128 v[208:211], v136 offset:2048
	v_mfma_f32_32x32x16_bf16 v[82:97], v[204:207], v[228:231], v[82:97]
	ds_read_b128 v[216:219], v136 offset:4096
	ds_read_b128 v[224:227], v136 offset:6144
	v_mfma_f32_32x32x16_bf16 v[66:81], v[204:207], v[236:239], v[66:81]
	v_mfma_f32_32x32x16_bf16 v[50:65], v[212:215], v[228:231], v[50:65]
	v_mfma_f32_32x32x16_bf16 v[34:49], v[212:215], v[236:239], v[34:49]
	v_mfma_f32_32x32x16_bf16 v[18:33], v[220:223], v[228:231], v[18:33]
	v_mfma_f32_32x32x16_bf16 v[2:17], v[220:223], v[236:239], v[2:17]
	s_waitcnt vmcnt(6) lgkmcnt(0)
	s_barrier
	s_setprio 1
	s_mov_b32 s34, s73
	s_add_u32 s73, s34, 0x6000
	s_cmp_lt_u32 s73, 0x12000
	s_cselect_b32 s73, s73, 0
	v_mfma_f32_32x32x16_bf16 v[114:129], v[166:169], v[232:235], v[114:129]
	ds_read_b128 v[162:165], v138 offset:0
	ds_read_b128 v[228:231], v139 offset:0
	v_mfma_f32_32x32x16_bf16 v[98:113], v[166:169], v[240:243], v[98:113]
	ds_read_b128 v[236:239], v139 offset:2048
	ds_read_b128 v[204:207], v138 offset:2048
	v_add_u32_e32 v136, s34, v134
	v_add_u32_e32 v137, s34, v135
	v_mfma_f32_32x32x16_bf16 v[82:97], v[208:211], v[232:235], v[82:97]
	ds_read_b128 v[212:215], v138 offset:4096
	ds_read_b128 v[220:223], v138 offset:6144
	v_mfma_f32_32x32x16_bf16 v[66:81], v[208:211], v[240:243], v[66:81]
	v_add_u32_e32 v138, s73, v132
	v_add_u32_e32 v139, s73, v133
	v_mfma_f32_32x32x16_bf16 v[50:65], v[216:219], v[232:235], v[50:65]
	v_mfma_f32_32x32x16_bf16 v[34:49], v[216:219], v[240:243], v[34:49]
	v_mfma_f32_32x32x16_bf16 v[18:33], v[224:227], v[232:235], v[18:33]
	v_mfma_f32_32x32x16_bf16 v[2:17], v[224:227], v[240:243], v[2:17]
	s_setprio 0
	s_waitcnt lgkmcnt(0)
	v_mfma_f32_32x32x16_bf16 v[114:129], v[162:165], v[228:231], v[114:129]
	ds_read_b128 v[166:169], v136 offset:0
	ds_read_b128 v[232:235], v137 offset:0
	s_add_i32 s9, s9, 1
	v_mfma_f32_32x32x16_bf16 v[98:113], v[162:165], v[236:239], v[98:113]
	ds_read_b128 v[240:243], v137 offset:2048
	ds_read_b128 v[208:211], v136 offset:2048
	v_mfma_f32_32x32x16_bf16 v[82:97], v[204:207], v[228:231], v[82:97]
	ds_read_b128 v[216:219], v136 offset:4096
	ds_read_b128 v[224:227], v136 offset:6144
	v_mfma_f32_32x32x16_bf16 v[66:81], v[204:207], v[236:239], v[66:81]
	v_mfma_f32_32x32x16_bf16 v[50:65], v[212:215], v[228:231], v[50:65]
	v_mfma_f32_32x32x16_bf16 v[34:49], v[212:215], v[236:239], v[34:49]
	v_mfma_f32_32x32x16_bf16 v[18:33], v[220:223], v[228:231], v[18:33]
	v_mfma_f32_32x32x16_bf16 v[2:17], v[220:223], v[236:239], v[2:17]
	s_waitcnt vmcnt(0) lgkmcnt(0)
	s_barrier
	s_setprio 1
	s_mov_b32 s34, s73
	s_add_u32 s73, s34, 0x6000
	s_cmp_lt_u32 s73, 0x12000
	s_cselect_b32 s73, s73, 0
	v_mfma_f32_32x32x16_bf16 v[114:129], v[166:169], v[232:235], v[114:129]
	ds_read_b128 v[162:165], v138 offset:0
	ds_read_b128 v[228:231], v139 offset:0
	v_mfma_f32_32x32x16_bf16 v[98:113], v[166:169], v[240:243], v[98:113]
	ds_read_b128 v[236:239], v139 offset:2048
	ds_read_b128 v[204:207], v138 offset:2048
	v_add_u32_e32 v136, s34, v134
	v_add_u32_e32 v137, s34, v135
	v_mfma_f32_32x32x16_bf16 v[82:97], v[208:211], v[232:235], v[82:97]
	ds_read_b128 v[212:215], v138 offset:4096
	ds_read_b128 v[220:223], v138 offset:6144
	v_mfma_f32_32x32x16_bf16 v[66:81], v[208:211], v[240:243], v[66:81]
	v_add_u32_e32 v138, s73, v132
	v_add_u32_e32 v139, s73, v133
	v_mfma_f32_32x32x16_bf16 v[50:65], v[216:219], v[232:235], v[50:65]
	v_mfma_f32_32x32x16_bf16 v[34:49], v[216:219], v[240:243], v[34:49]
	v_mfma_f32_32x32x16_bf16 v[18:33], v[224:227], v[232:235], v[18:33]
	v_mfma_f32_32x32x16_bf16 v[2:17], v[224:227], v[240:243], v[2:17]
	s_setprio 0
	s_waitcnt lgkmcnt(0)
	v_mfma_f32_32x32x16_bf16 v[114:129], v[162:165], v[228:231], v[114:129]
	ds_read_b128 v[166:169], v136 offset:0
	ds_read_b128 v[232:235], v137 offset:0
	s_add_i32 s9, s9, 1
	v_mfma_f32_32x32x16_bf16 v[98:113], v[162:165], v[236:239], v[98:113]
	ds_read_b128 v[240:243], v137 offset:2048
	ds_read_b128 v[208:211], v136 offset:2048
	v_mfma_f32_32x32x16_bf16 v[82:97], v[204:207], v[228:231], v[82:97]
	ds_read_b128 v[216:219], v136 offset:4096
	ds_read_b128 v[224:227], v136 offset:6144
	v_mfma_f32_32x32x16_bf16 v[66:81], v[204:207], v[236:239], v[66:81]
	v_mfma_f32_32x32x16_bf16 v[50:65], v[212:215], v[228:231], v[50:65]
	v_mfma_f32_32x32x16_bf16 v[34:49], v[212:215], v[236:239], v[34:49]
	v_mfma_f32_32x32x16_bf16 v[18:33], v[220:223], v[228:231], v[18:33]
	v_mfma_f32_32x32x16_bf16 v[2:17], v[220:223], v[236:239], v[2:17]
	s_waitcnt lgkmcnt(0)
	v_mfma_f32_32x32x16_bf16 v[114:129], v[166:169], v[232:235], v[114:129]
	v_mfma_f32_32x32x16_bf16 v[98:113], v[166:169], v[240:243], v[98:113]
	v_mfma_f32_32x32x16_bf16 v[82:97], v[208:211], v[232:235], v[82:97]
	v_mfma_f32_32x32x16_bf16 v[66:81], v[208:211], v[240:243], v[66:81]
	v_mfma_f32_32x32x16_bf16 v[50:65], v[216:219], v[232:235], v[50:65]
	v_mfma_f32_32x32x16_bf16 v[34:49], v[216:219], v[240:243], v[34:49]
	v_mfma_f32_32x32x16_bf16 v[18:33], v[224:227], v[232:235], v[18:33]
	v_mfma_f32_32x32x16_bf16 v[2:17], v[224:227], v[240:243], v[2:17]
	s_mov_b32 s14, 31
	s_lshl_b64 s[12:13], s[14:15], 13
	s_movk_i32 s34, 0x7800
	s_movk_i32 s72, 0x6000
	s_mov_b32 s73, 0xc000
	s_setprio 0
	s_movk_i32 s74, 0x104
	s_mov_b32 s75, 0x42ce8ed0
	s_mov_b32 s76, 0xbfb8aa3b
	s_mov_b32 s77, 0x1d730000
	v_mov_b32_e32 v0, v171
	s_barrier
	s_waitcnt vmcnt(4)
	v_lshrrev_b32_e32 v130, 1, v0
	v_and_b32_e32 v130, 0xfffffc0, v130
	v_lshrrev_b32_e32 v131, 3, v0
	v_and_or_b32 v130, v131, 4, v130
	v_and_b32_e32 v0, 0x5f, v0
	v_mul_lo_u32 v130, v130, s53
	v_lshl_add_u32 v0, v0, 2, v130
	s_barrier
	ds_write2_b32 v0, v114, v98 offset1:32
	ds_write2_b32 v0, v115, v99 offset0:132 offset1:164
	v_add_u32_e32 v98, 0x400, v0
	ds_write2_b32 v98, v116, v100 offset0:8 offset1:40
	ds_write2_b32 v98, v117, v101 offset0:140 offset1:172
	v_add_u32_e32 v98, 0x1000, v0
	ds_write2_b32 v98, v118, v102 offset0:32 offset1:64
	ds_write2_b32 v98, v119, v103 offset0:164 offset1:196
	v_add_u32_e32 v98, 0x1400, v0
	ds_write2_b32 v98, v120, v104 offset0:40 offset1:72
	ds_write2_b32 v98, v121, v105 offset0:172 offset1:204
	v_add_u32_e32 v98, 0x2000, v0
	ds_write2_b32 v98, v122, v106 offset0:64 offset1:96
	ds_write2_b32 v98, v123, v107 offset0:196 offset1:228
	v_add_u32_e32 v98, 0x2400, v0
	ds_write2_b32 v98, v124, v108 offset0:72 offset1:104
	ds_write2_b32 v98, v125, v109 offset0:204 offset1:236
	v_add_u32_e32 v98, 0x3000, v0
	ds_write2_b32 v98, v126, v110 offset0:96 offset1:128
	v_add_u32_e32 v98, 0x3200, v0
	ds_write2_b32 v98, v127, v111 offset0:100 offset1:132
	v_add_u32_e32 v98, 0x3400, v0
	ds_write2_b32 v98, v128, v112 offset0:104 offset1:136
	v_add_u32_e32 v98, 0x3600, v0
	ds_write2_b32 v98, v129, v113 offset0:108 offset1:140
	v_add_u32_e32 v98, 0x4000, v0
	ds_write2_b32 v98, v82, v66 offset0:128 offset1:160
	v_add_u32_e32 v66, 0x4400, v0
	ds_write2_b32 v66, v83, v67 offset0:4 offset1:36
	ds_write2_b32 v66, v84, v68 offset0:136 offset1:168
	v_add_u32_e32 v66, 0x4800, v0
	ds_write2_b32 v66, v85, v69 offset0:12 offset1:44
	v_add_u32_e32 v66, 0x5000, v0
	ds_write2_b32 v66, v86, v70 offset0:160 offset1:192
	v_add_u32_e32 v66, 0x5400, v0
	ds_write2_b32 v66, v87, v71 offset0:36 offset1:68
	ds_write2_b32 v66, v88, v72 offset0:168 offset1:200
	v_add_u32_e32 v66, 0x5800, v0
	ds_write2_b32 v66, v89, v73 offset0:44 offset1:76
	v_add_u32_e32 v66, 0x6000, v0
	ds_write2_b32 v66, v90, v74 offset0:192 offset1:224
	v_add_u32_e32 v66, 0x6400, v0
	ds_write2_b32 v66, v91, v75 offset0:68 offset1:100
	ds_write2_b32 v66, v92, v76 offset0:200 offset1:232
	v_add_u32_e32 v66, 0x6800, v0
	ds_write2_b32 v66, v93, v77 offset0:76 offset1:108
	v_add_u32_e32 v66, 0x7200, v0
	ds_write2_b32 v66, v94, v78 offset0:96 offset1:128
	v_add_u32_e32 v66, 0x7400, v0
	ds_write2_b32 v66, v95, v79 offset0:100 offset1:132
	v_add_u32_e32 v66, 0x7600, v0
	v_add_u32_e32 v0, 0x7800, v0
	v_mov_b32_e32 v74, v171
	ds_write2_b32 v66, v96, v80 offset0:104 offset1:136
	ds_write2_b32 v0, v97, v81 offset0:108 offset1:140
	s_waitcnt lgkmcnt(0)
	s_barrier
	s_lshl_b32 s8, s8, 7
	v_lshlrev_b32_e32 v75, 3, v74
	v_and_b32_e32 v0, 0x78, v75
	v_or_b32_e32 v0, s8, v0
	v_lshl_add_u64 v[70:71], v[0:1], 2, s[6:7]
	global_load_dwordx4 v[66:69], v[70:71], off
	s_nop 0
	global_load_dwordx4 v[70:73], v[70:71], off offset:16
	v_ashrrev_i32_e32 v76, 4, v74
	v_lshrrev_b32_e32 v77, 5, v0
	v_and_b32_e32 v0, 24, v75
	v_mul_lo_u32 v75, v76, s53
	v_and_b32_e32 v74, 15, v74
	v_readlane_b32 s0, v252, 46
	s_lshl_b32 s9, s11, 8
	v_lshl_add_u32 v78, v74, 5, v75
	v_lshlrev_b32_e32 v79, 1, v76
	s_mov_b32 s11, 0
	v_lshlrev_b32_e32 v74, 1, v0
	v_readlane_b32 s1, v252, 47
	s_waitcnt vmcnt(0)

.Lg357_loop:
	s_setprio 0
	s_waitcnt lgkmcnt(0)
	v_mfma_f32_32x32x16_bf16 v[114:129], v[162:165], v[228:231], v[114:129]
	ds_read_b128 v[166:169], v136 offset:0
	ds_read_b128 v[232:235], v137 offset:0
	s_add_i32 s7, s7, 1
	s_add_i32 s14, s7, 2
	s_lshl_b64 s[10:11], s[14:15], 14
	s_add_u32 s10, s10, s74
	s_addc_u32 s11, s11, s75
	v_mfma_f32_32x32x16_bf16 v[98:113], v[162:165], v[236:239], v[98:113]
	ds_read_b128 v[240:243], v137 offset:2048
	ds_read_b128 v[208:211], v136 offset:2048
	v_mfma_f32_32x32x16_bf16 v[82:97], v[204:207], v[228:231], v[82:97]
	ds_read_b128 v[216:219], v136 offset:4096
	ds_read_b128 v[224:227], v136 offset:6144
	v_mfma_f32_32x32x16_bf16 v[66:81], v[204:207], v[236:239], v[66:81]
	v_mfma_f32_32x32x16_bf16 v[50:65], v[212:215], v[228:231], v[50:65]
	v_mfma_f32_32x32x16_bf16 v[34:49], v[212:215], v[236:239], v[34:49]
	v_mfma_f32_32x32x16_bf16 v[18:33], v[220:223], v[228:231], v[18:33]
	v_mfma_f32_32x32x16_bf16 v[2:17], v[220:223], v[236:239], v[2:17]
	s_waitcnt vmcnt(6) lgkmcnt(0)
	s_barrier
	s_setprio 1
	s_add_u32 m0, s13, s72
	s_mov_b32 s13, s73
	s_add_u32 s73, s13, 0x6000
	s_cmp_lt_u32 s73, 0x12000
	s_cselect_b32 s73, s73, 0
	v_mfma_f32_32x32x16_bf16 v[114:129], v[166:169], v[232:235], v[114:129]
	ds_read_b128 v[162:165], v138 offset:0
	ds_read_b128 v[228:231], v139 offset:0
	v_mfma_f32_32x32x16_bf16 v[98:113], v[166:169], v[240:243], v[98:113]
	ds_read_b128 v[236:239], v139 offset:2048
	ds_read_b128 v[204:207], v138 offset:2048
	v_add_u32_e32 v136, s13, v134
	v_add_u32_e32 v137, s13, v135
	v_mfma_f32_32x32x16_bf16 v[82:97], v[208:211], v[232:235], v[82:97]
	ds_read_b128 v[212:215], v138 offset:4096
	ds_read_b128 v[220:223], v138 offset:6144
	v_mfma_f32_32x32x16_bf16 v[66:81], v[208:211], v[240:243], v[66:81]
	global_load_lds_dwordx4 v140, s[10:11]
	s_add_u32 m0, m0, 0x1000
	s_add_u32 s10, s10, 0x1000
	s_addc_u32 s11, s11, 0
	v_add_u32_e32 v138, s73, v132
	v_add_u32_e32 v139, s73, v133
	v_mfma_f32_32x32x16_bf16 v[50:65], v[216:219], v[232:235], v[50:65]
	global_load_lds_dwordx4 v140, s[10:11]
	s_add_u32 m0, m0, 0x1000
	s_add_u32 s10, s10, 0x1000
	s_addc_u32 s11, s11, 0
	v_mfma_f32_32x32x16_bf16 v[34:49], v[216:219], v[240:243], v[34:49]
	global_load_lds_dwordx4 v140, s[10:11]
	s_add_u32 m0, m0, 0x1000
	s_add_u32 s10, s10, 0x1000
	s_addc_u32 s11, s11, 0
	v_mfma_f32_32x32x16_bf16 v[18:33], v[224:227], v[232:235], v[18:33]
	global_load_lds_dwordx4 v140, s[10:11]
	s_add_u32 m0, m0, 0x1000
	s_lshl_b64 s[10:11], s[14:15], 13
	s_add_u32 s10, s10, s76
	s_addc_u32 s11, s11, s77
	v_mfma_f32_32x32x16_bf16 v[2:17], v[224:227], v[240:243], v[2:17]
	global_load_lds_dwordx4 v140, s[10:11]
	s_add_u32 m0, m0, 0x1000
	s_add_u32 s10, s10, 0x1000
	s_addc_u32 s11, s11, 0
	s_nop 0
	global_load_lds_dwordx4 v140, s[10:11]
	s_cmp_lg_u32 s7, 29
	s_cbranch_scc1 .Lg357_loop
	s_setprio 0
	s_waitcnt lgkmcnt(0)
	v_mfma_f32_32x32x16_bf16 v[114:129], v[162:165], v[228:231], v[114:129]
	ds_read_b128 v[166:169], v136 offset:0
	ds_read_b128 v[232:235], v137 offset:0
	s_add_i32 s7, s7, 1
	v_mfma_f32_32x32x16_bf16 v[98:113], v[162:165], v[236:239], v[98:113]
	ds_read_b128 v[240:243], v137 offset:2048
	ds_read_b128 v[208:211], v136 offset:2048
	v_mfma_f32_32x32x16_bf16 v[82:97], v[204:207], v[228:231], v[82:97]
	ds_read_b128 v[216:219], v136 offset:4096
	ds_read_b128 v[224:227], v136 offset:6144
	v_mfma_f32_32x32x16_bf16 v[66:81], v[204:207], v[236:239], v[66:81]
	v_mfma_f32_32x32x16_bf16 v[50:65], v[212:215], v[228:231], v[50:65]
	v_mfma_f32_32x32x16_bf16 v[34:49], v[212:215], v[236:239], v[34:49]
	v_mfma_f32_32x32x16_bf16 v[18:33], v[220:223], v[228:231], v[18:33]
	v_mfma_f32_32x32x16_bf16 v[2:17], v[220:223], v[236:239], v[2:17]
	s_waitcnt vmcnt(6) lgkmcnt(0)
	s_barrier
	s_setprio 1
	s_mov_b32 s13, s73
	s_add_u32 s73, s13, 0x6000
	s_cmp_lt_u32 s73, 0x12000
	s_cselect_b32 s73, s73, 0
	v_mfma_f32_32x32x16_bf16 v[114:129], v[166:169], v[232:235], v[114:129]
	ds_read_b128 v[162:165], v138 offset:0
	ds_read_b128 v[228:231], v139 offset:0
	v_mfma_f32_32x32x16_bf16 v[98:113], v[166:169], v[240:243], v[98:113]
	ds_read_b128 v[236:239], v139 offset:2048
	ds_read_b128 v[204:207], v138 offset:2048
	v_add_u32_e32 v136, s13, v134
	v_add_u32_e32 v137, s13, v135
	v_mfma_f32_32x32x16_bf16 v[82:97], v[208:211], v[232:235], v[82:97]
	ds_read_b128 v[212:215], v138 offset:4096
	ds_read_b128 v[220:223], v138 offset:6144
	v_mfma_f32_32x32x16_bf16 v[66:81], v[208:211], v[240:243], v[66:81]
	v_add_u32_e32 v138, s73, v132
	v_add_u32_e32 v139, s73, v133
	v_mfma_f32_32x32x16_bf16 v[50:65], v[216:219], v[232:235], v[50:65]
	v_mfma_f32_32x32x16_bf16 v[34:49], v[216:219], v[240:243], v[34:49]
	v_mfma_f32_32x32x16_bf16 v[18:33], v[224:227], v[232:235], v[18:33]
	v_mfma_f32_32x32x16_bf16 v[2:17], v[224:227], v[240:243], v[2:17]
	s_setprio 0
	s_waitcnt lgkmcnt(0)
	v_mfma_f32_32x32x16_bf16 v[114:129], v[162:165], v[228:231], v[114:129]
	ds_read_b128 v[166:169], v136 offset:0
	ds_read_b128 v[232:235], v137 offset:0
	s_add_i32 s7, s7, 1
	v_mfma_f32_32x32x16_bf16 v[98:113], v[162:165], v[236:239], v[98:113]
	ds_read_b128 v[240:243], v137 offset:2048
	ds_read_b128 v[208:211], v136 offset:2048
	v_mfma_f32_32x32x16_bf16 v[82:97], v[204:207], v[228:231], v[82:97]
	ds_read_b128 v[216:219], v136 offset:4096
	ds_read_b128 v[224:227], v136 offset:6144
	v_mfma_f32_32x32x16_bf16 v[66:81], v[204:207], v[236:239], v[66:81]
	v_mfma_f32_32x32x16_bf16 v[50:65], v[212:215], v[228:231], v[50:65]
	v_mfma_f32_32x32x16_bf16 v[34:49], v[212:215], v[236:239], v[34:49]
	v_mfma_f32_32x32x16_bf16 v[18:33], v[220:223], v[228:231], v[18:33]
	v_mfma_f32_32x32x16_bf16 v[2:17], v[220:223], v[236:239], v[2:17]
	s_waitcnt vmcnt(0) lgkmcnt(0)
	s_barrier
	s_setprio 1
	s_mov_b32 s13, s73
	s_add_u32 s73, s13, 0x6000
	s_cmp_lt_u32 s73, 0x12000
	s_cselect_b32 s73, s73, 0
	v_mfma_f32_32x32x16_bf16 v[114:129], v[166:169], v[232:235], v[114:129]
	ds_read_b128 v[162:165], v138 offset:0
	ds_read_b128 v[228:231], v139 offset:0
	v_mfma_f32_32x32x16_bf16 v[98:113], v[166:169], v[240:243], v[98:113]
	ds_read_b128 v[236:239], v139 offset:2048
	ds_read_b128 v[204:207], v138 offset:2048
	v_add_u32_e32 v136, s13, v134
	v_add_u32_e32 v137, s13, v135
	v_mfma_f32_32x32x16_bf16 v[82:97], v[208:211], v[232:235], v[82:97]
	ds_read_b128 v[212:215], v138 offset:4096
	ds_read_b128 v[220:223], v138 offset:6144
	v_mfma_f32_32x32x16_bf16 v[66:81], v[208:211], v[240:243], v[66:81]
	v_add_u32_e32 v138, s73, v132
	v_add_u32_e32 v139, s73, v133
	v_mfma_f32_32x32x16_bf16 v[50:65], v[216:219], v[232:235], v[50:65]
	v_mfma_f32_32x32x16_bf16 v[34:49], v[216:219], v[240:243], v[34:49]
	v_mfma_f32_32x32x16_bf16 v[18:33], v[224:227], v[232:235], v[18:33]
	v_mfma_f32_32x32x16_bf16 v[2:17], v[224:227], v[240:243], v[2:17]
	s_setprio 0
	s_waitcnt lgkmcnt(0)
	v_mfma_f32_32x32x16_bf16 v[114:129], v[162:165], v[228:231], v[114:129]
	ds_read_b128 v[166:169], v136 offset:0
	ds_read_b128 v[232:235], v137 offset:0
	s_add_i32 s7, s7, 1
	v_mfma_f32_32x32x16_bf16 v[98:113], v[162:165], v[236:239], v[98:113]
	ds_read_b128 v[240:243], v137 offset:2048
	ds_read_b128 v[208:211], v136 offset:2048
	v_mfma_f32_32x32x16_bf16 v[82:97], v[204:207], v[228:231], v[82:97]
	ds_read_b128 v[216:219], v136 offset:4096
	ds_read_b128 v[224:227], v136 offset:6144
	v_mfma_f32_32x32x16_bf16 v[66:81], v[204:207], v[236:239], v[66:81]
	v_mfma_f32_32x32x16_bf16 v[50:65], v[212:215], v[228:231], v[50:65]
	v_mfma_f32_32x32x16_bf16 v[34:49], v[212:215], v[236:239], v[34:49]
	v_mfma_f32_32x32x16_bf16 v[18:33], v[220:223], v[228:231], v[18:33]
	v_mfma_f32_32x32x16_bf16 v[2:17], v[220:223], v[236:239], v[2:17]
	s_waitcnt lgkmcnt(0)
	v_mfma_f32_32x32x16_bf16 v[114:129], v[166:169], v[232:235], v[114:129]
	v_mfma_f32_32x32x16_bf16 v[98:113], v[166:169], v[240:243], v[98:113]
	v_mfma_f32_32x32x16_bf16 v[82:97], v[208:211], v[232:235], v[82:97]
	v_mfma_f32_32x32x16_bf16 v[66:81], v[208:211], v[240:243], v[66:81]
	v_mfma_f32_32x32x16_bf16 v[50:65], v[216:219], v[232:235], v[50:65]
	v_mfma_f32_32x32x16_bf16 v[34:49], v[216:219], v[240:243], v[34:49]
	v_mfma_f32_32x32x16_bf16 v[18:33], v[224:227], v[232:235], v[18:33]
	v_mfma_f32_32x32x16_bf16 v[2:17], v[224:227], v[240:243], v[2:17]
	s_mov_b32 s14, 31
	s_lshl_b64 s[10:11], s[14:15], 13
	s_movk_i32 s13, 0x7800
	s_movk_i32 s72, 0x6000
	s_mov_b32 s73, 0xc000
	s_setprio 0
	s_movk_i32 s74, 0x104
	s_mov_b32 s75, 0x42ce8ed0
	s_mov_b32 s76, 0xbfb8aa3b
	s_mov_b32 s77, 0x1d730000
	v_mov_b32_e32 v0, v171
	s_barrier
	s_waitcnt vmcnt(4)
	v_lshrrev_b32_e32 v130, 1, v0
	v_and_b32_e32 v130, 0xfffffc0, v130
	v_lshrrev_b32_e32 v131, 3, v0
	v_and_or_b32 v130, v131, 4, v130
	v_and_b32_e32 v0, 0x5f, v0
	v_mul_lo_u32 v130, v130, s53
	v_lshl_add_u32 v0, v0, 2, v130
	s_barrier
	ds_write2_b32 v0, v114, v98 offset1:32
	ds_write2_b32 v0, v115, v99 offset0:132 offset1:164
	v_add_u32_e32 v98, 0x400, v0
	ds_write2_b32 v98, v116, v100 offset0:8 offset1:40
	ds_write2_b32 v98, v117, v101 offset0:140 offset1:172
	v_add_u32_e32 v98, 0x1000, v0
	ds_write2_b32 v98, v118, v102 offset0:32 offset1:64
	ds_write2_b32 v98, v119, v103 offset0:164 offset1:196
	v_add_u32_e32 v98, 0x1400, v0
	ds_write2_b32 v98, v120, v104 offset0:40 offset1:72
	ds_write2_b32 v98, v121, v105 offset0:172 offset1:204
	v_add_u32_e32 v98, 0x2000, v0
	ds_write2_b32 v98, v122, v106 offset0:64 offset1:96
	ds_write2_b32 v98, v123, v107 offset0:196 offset1:228
	v_add_u32_e32 v98, 0x2400, v0
	ds_write2_b32 v98, v124, v108 offset0:72 offset1:104
	ds_write2_b32 v98, v125, v109 offset0:204 offset1:236
	v_add_u32_e32 v98, 0x3000, v0
	ds_write2_b32 v98, v126, v110 offset0:96 offset1:128
	v_add_u32_e32 v98, 0x3200, v0
	ds_write2_b32 v98, v127, v111 offset0:100 offset1:132
	v_add_u32_e32 v98, 0x3400, v0
	ds_write2_b32 v98, v128, v112 offset0:104 offset1:136
	v_add_u32_e32 v98, 0x3600, v0
	ds_write2_b32 v98, v129, v113 offset0:108 offset1:140
	v_add_u32_e32 v98, 0x4000, v0
	ds_write2_b32 v98, v82, v66 offset0:128 offset1:160
	v_add_u32_e32 v66, 0x4400, v0
	ds_write2_b32 v66, v83, v67 offset0:4 offset1:36
	ds_write2_b32 v66, v84, v68 offset0:136 offset1:168
	v_add_u32_e32 v66, 0x4800, v0
	ds_write2_b32 v66, v85, v69 offset0:12 offset1:44
	v_add_u32_e32 v66, 0x5000, v0
	s_lshl_b32 s13, s9, 8
	ds_write2_b32 v66, v86, v70 offset0:160 offset1:192
	v_add_u32_e32 v66, 0x5400, v0
	s_lshl_b32 s34, s6, 7
	ds_write2_b32 v66, v87, v71 offset0:36 offset1:68
	ds_write2_b32 v66, v88, v72 offset0:168 offset1:200
	v_add_u32_e32 v66, 0x5800, v0
	s_add_i32 s6, s13, 0xffffe000
	ds_write2_b32 v66, v89, v73 offset0:44 offset1:76
	v_add_u32_e32 v66, 0x6000, v0
	s_lshr_b32 s6, s6, 12
	ds_write2_b32 v66, v90, v74 offset0:192 offset1:224
	v_add_u32_e32 v66, 0x6400, v0
	s_mulk_i32 s6, 0x1800
	ds_write2_b32 v66, v91, v75 offset0:68 offset1:100
	ds_write2_b32 v66, v92, v76 offset0:200 offset1:232
	v_add_u32_e32 v66, 0x6800, v0
	s_addk_i32 s6, 0x1800
	ds_write2_b32 v66, v93, v77 offset0:76 offset1:108
	v_add_u32_e32 v66, 0x7200, v0
	s_cmp_gt_u32 s8, 31
	ds_write2_b32 v66, v94, v78 offset0:96 offset1:128
	v_add_u32_e32 v66, 0x7400, v0
	s_cselect_b32 s14, s6, 0
	ds_write2_b32 v66, v95, v79 offset0:100 offset1:132
	v_add_u32_e32 v66, 0x7600, v0
	v_add_u32_e32 v0, 0x7800, v0
	v_mov_b32_e32 v76, v171
	s_lshl_b64 s[6:7], s[14:15], 2
	ds_write2_b32 v66, v96, v80 offset0:104 offset1:136
	ds_write2_b32 v0, v97, v81 offset0:108 offset1:140
	s_waitcnt lgkmcnt(0)
	s_barrier
	s_add_u32 s6, s61, s6
	v_lshlrev_b32_e32 v0, 3, v76
	v_and_b32_e32 v0, 0x78, v0
	s_addc_u32 s7, s79, s7
	v_or_b32_e32 v0, s34, v0
	s_add_u32 s8, s6, 0x1d642000
	s_addc_u32 s9, s7, 0
	v_lshlrev_b64 v[74:75], 2, v[0:1]
	v_lshl_add_u64 v[70:71], s[8:9], 0, v[74:75]
	global_load_dwordx4 v[66:69], v[70:71], off offset:16
	s_nop 0
	global_load_dwordx4 v[70:73], v[70:71], off
	v_ashrrev_i32_e32 v90, 4, v76
	v_lshl_add_u64 v[82:83], s[56:57], 0, v[74:75]
	v_mul_lo_u32 v74, v90, s53
	v_and_b32_e32 v75, 15, v76
	s_mov_b32 s14, 0
	v_lshl_add_u32 v91, v75, 5, v74
	v_lshlrev_b32_e32 v92, 1, v90
	s_branch .LBB0_360

.Lg432_loop:
	s_setprio 0
	s_waitcnt lgkmcnt(0)
	v_mfma_f32_32x32x16_bf16 v[114:129], v[162:165], v[228:231], v[114:129]
	ds_read_b128 v[166:169], v136 offset:0
	ds_read_b128 v[232:235], v137 offset:0
	s_add_i32 s6, s6, 1
	s_add_i32 s14, s6, 2
	s_lshl_b64 s[12:13], s[14:15], 14
	s_add_u32 s12, s12, s74
	s_addc_u32 s13, s13, s75
	v_mfma_f32_32x32x16_bf16 v[98:113], v[162:165], v[236:239], v[98:113]
	ds_read_b128 v[240:243], v137 offset:2048
	ds_read_b128 v[208:211], v136 offset:2048
	v_mfma_f32_32x32x16_bf16 v[82:97], v[204:207], v[228:231], v[82:97]
	ds_read_b128 v[216:219], v136 offset:4096
	ds_read_b128 v[224:227], v136 offset:6144
	v_mfma_f32_32x32x16_bf16 v[66:81], v[204:207], v[236:239], v[66:81]
	v_mfma_f32_32x32x16_bf16 v[50:65], v[212:215], v[228:231], v[50:65]
	v_mfma_f32_32x32x16_bf16 v[34:49], v[212:215], v[236:239], v[34:49]
	v_mfma_f32_32x32x16_bf16 v[18:33], v[220:223], v[228:231], v[18:33]
	v_mfma_f32_32x32x16_bf16 v[2:17], v[220:223], v[236:239], v[2:17]
	s_waitcnt vmcnt(6) lgkmcnt(0)
	s_barrier
	s_setprio 1
	s_add_u32 m0, s7, s72
	s_mov_b32 s7, s73
	s_add_u32 s73, s7, 0x6000
	s_cmp_lt_u32 s73, 0x12000
	s_cselect_b32 s73, s73, 0
	v_mfma_f32_32x32x16_bf16 v[114:129], v[166:169], v[232:235], v[114:129]
	ds_read_b128 v[162:165], v138 offset:0
	ds_read_b128 v[228:231], v139 offset:0
	v_mfma_f32_32x32x16_bf16 v[98:113], v[166:169], v[240:243], v[98:113]
	ds_read_b128 v[236:239], v139 offset:2048
	ds_read_b128 v[204:207], v138 offset:2048
	v_add_u32_e32 v136, s7, v134
	v_add_u32_e32 v137, s7, v135
	v_mfma_f32_32x32x16_bf16 v[82:97], v[208:211], v[232:235], v[82:97]
	ds_read_b128 v[212:215], v138 offset:4096
	ds_read_b128 v[220:223], v138 offset:6144
	v_mfma_f32_32x32x16_bf16 v[66:81], v[208:211], v[240:243], v[66:81]
	global_load_lds_dwordx4 v140, s[12:13]
	s_add_u32 m0, m0, 0x1000
	s_add_u32 s12, s12, 0x1000
	s_addc_u32 s13, s13, 0
	v_add_u32_e32 v138, s73, v132
	v_add_u32_e32 v139, s73, v133
	v_mfma_f32_32x32x16_bf16 v[50:65], v[216:219], v[232:235], v[50:65]
	global_load_lds_dwordx4 v140, s[12:13]
	s_add_u32 m0, m0, 0x1000
	s_add_u32 s12, s12, 0x1000
	s_addc_u32 s13, s13, 0
	v_mfma_f32_32x32x16_bf16 v[34:49], v[216:219], v[240:243], v[34:49]
	global_load_lds_dwordx4 v140, s[12:13]
	s_add_u32 m0, m0, 0x1000
	s_add_u32 s12, s12, 0x1000
	s_addc_u32 s13, s13, 0
	v_mfma_f32_32x32x16_bf16 v[18:33], v[224:227], v[232:235], v[18:33]
	global_load_lds_dwordx4 v140, s[12:13]
	s_add_u32 m0, m0, 0x1000
	s_lshl_b64 s[12:13], s[14:15], 13
	s_add_u32 s12, s12, s76
	s_addc_u32 s13, s13, s77
	v_mfma_f32_32x32x16_bf16 v[2:17], v[224:227], v[240:243], v[2:17]
	global_load_lds_dwordx4 v140, s[12:13]
	s_add_u32 m0, m0, 0x1000
	s_add_u32 s12, s12, 0x1000
	s_addc_u32 s13, s13, 0
	s_nop 0
	global_load_lds_dwordx4 v140, s[12:13]
	s_cmp_lg_u32 s6, 29
	s_cbranch_scc1 .Lg432_loop
	s_setprio 0
	s_waitcnt lgkmcnt(0)
	v_mfma_f32_32x32x16_bf16 v[114:129], v[162:165], v[228:231], v[114:129]
	ds_read_b128 v[166:169], v136 offset:0
	ds_read_b128 v[232:235], v137 offset:0
	s_add_i32 s6, s6, 1
	v_mfma_f32_32x32x16_bf16 v[98:113], v[162:165], v[236:239], v[98:113]
	ds_read_b128 v[240:243], v137 offset:2048
	ds_read_b128 v[208:211], v136 offset:2048
	v_mfma_f32_32x32x16_bf16 v[82:97], v[204:207], v[228:231], v[82:97]
	ds_read_b128 v[216:219], v136 offset:4096
	ds_read_b128 v[224:227], v136 offset:6144
	v_mfma_f32_32x32x16_bf16 v[66:81], v[204:207], v[236:239], v[66:81]
	v_mfma_f32_32x32x16_bf16 v[50:65], v[212:215], v[228:231], v[50:65]
	v_mfma_f32_32x32x16_bf16 v[34:49], v[212:215], v[236:239], v[34:49]
	v_mfma_f32_32x32x16_bf16 v[18:33], v[220:223], v[228:231], v[18:33]
	v_mfma_f32_32x32x16_bf16 v[2:17], v[220:223], v[236:239], v[2:17]
	s_waitcnt vmcnt(6) lgkmcnt(0)
	s_barrier
	s_setprio 1
	s_mov_b32 s7, s73
	s_add_u32 s73, s7, 0x6000
	s_cmp_lt_u32 s73, 0x12000
	s_cselect_b32 s73, s73, 0
	v_mfma_f32_32x32x16_bf16 v[114:129], v[166:169], v[232:235], v[114:129]
	ds_read_b128 v[162:165], v138 offset:0
	ds_read_b128 v[228:231], v139 offset:0
	v_mfma_f32_32x32x16_bf16 v[98:113], v[166:169], v[240:243], v[98:113]
	ds_read_b128 v[236:239], v139 offset:2048
	ds_read_b128 v[204:207], v138 offset:2048
	v_add_u32_e32 v136, s7, v134
	v_add_u32_e32 v137, s7, v135
	v_mfma_f32_32x32x16_bf16 v[82:97], v[208:211], v[232:235], v[82:97]
	ds_read_b128 v[212:215], v138 offset:4096
	ds_read_b128 v[220:223], v138 offset:6144
	v_mfma_f32_32x32x16_bf16 v[66:81], v[208:211], v[240:243], v[66:81]
	v_add_u32_e32 v138, s73, v132
	v_add_u32_e32 v139, s73, v133
	v_mfma_f32_32x32x16_bf16 v[50:65], v[216:219], v[232:235], v[50:65]
	v_mfma_f32_32x32x16_bf16 v[34:49], v[216:219], v[240:243], v[34:49]
	v_mfma_f32_32x32x16_bf16 v[18:33], v[224:227], v[232:235], v[18:33]
	v_mfma_f32_32x32x16_bf16 v[2:17], v[224:227], v[240:243], v[2:17]
	s_setprio 0
	s_waitcnt lgkmcnt(0)
	v_mfma_f32_32x32x16_bf16 v[114:129], v[162:165], v[228:231], v[114:129]
	ds_read_b128 v[166:169], v136 offset:0
	ds_read_b128 v[232:235], v137 offset:0
	s_add_i32 s6, s6, 1
	v_mfma_f32_32x32x16_bf16 v[98:113], v[162:165], v[236:239], v[98:113]
	ds_read_b128 v[240:243], v137 offset:2048
	ds_read_b128 v[208:211], v136 offset:2048
	v_mfma_f32_32x32x16_bf16 v[82:97], v[204:207], v[228:231], v[82:97]
	ds_read_b128 v[216:219], v136 offset:4096
	ds_read_b128 v[224:227], v136 offset:6144
	v_mfma_f32_32x32x16_bf16 v[66:81], v[204:207], v[236:239], v[66:81]
	v_mfma_f32_32x32x16_bf16 v[50:65], v[212:215], v[228:231], v[50:65]
	v_mfma_f32_32x32x16_bf16 v[34:49], v[212:215], v[236:239], v[34:49]
	v_mfma_f32_32x32x16_bf16 v[18:33], v[220:223], v[228:231], v[18:33]
	v_mfma_f32_32x32x16_bf16 v[2:17], v[220:223], v[236:239], v[2:17]
	s_waitcnt vmcnt(0) lgkmcnt(0)
	s_barrier
	s_setprio 1
	s_mov_b32 s7, s73
	s_add_u32 s73, s7, 0x6000
	s_cmp_lt_u32 s73, 0x12000
	s_cselect_b32 s73, s73, 0
	v_mfma_f32_32x32x16_bf16 v[114:129], v[166:169], v[232:235], v[114:129]
	ds_read_b128 v[162:165], v138 offset:0
	ds_read_b128 v[228:231], v139 offset:0
	v_mfma_f32_32x32x16_bf16 v[98:113], v[166:169], v[240:243], v[98:113]
	ds_read_b128 v[236:239], v139 offset:2048
	ds_read_b128 v[204:207], v138 offset:2048
	v_add_u32_e32 v136, s7, v134
	v_add_u32_e32 v137, s7, v135
	v_mfma_f32_32x32x16_bf16 v[82:97], v[208:211], v[232:235], v[82:97]
	ds_read_b128 v[212:215], v138 offset:4096
	ds_read_b128 v[220:223], v138 offset:6144
	v_mfma_f32_32x32x16_bf16 v[66:81], v[208:211], v[240:243], v[66:81]
	v_add_u32_e32 v138, s73, v132
	v_add_u32_e32 v139, s73, v133
	v_mfma_f32_32x32x16_bf16 v[50:65], v[216:219], v[232:235], v[50:65]
	v_mfma_f32_32x32x16_bf16 v[34:49], v[216:219], v[240:243], v[34:49]
	v_mfma_f32_32x32x16_bf16 v[18:33], v[224:227], v[232:235], v[18:33]
	v_mfma_f32_32x32x16_bf16 v[2:17], v[224:227], v[240:243], v[2:17]
	s_setprio 0
	s_waitcnt lgkmcnt(0)
	v_mfma_f32_32x32x16_bf16 v[114:129], v[162:165], v[228:231], v[114:129]
	ds_read_b128 v[166:169], v136 offset:0
	ds_read_b128 v[232:235], v137 offset:0
	s_add_i32 s6, s6, 1
	v_mfma_f32_32x32x16_bf16 v[98:113], v[162:165], v[236:239], v[98:113]
	ds_read_b128 v[240:243], v137 offset:2048
	ds_read_b128 v[208:211], v136 offset:2048
	v_mfma_f32_32x32x16_bf16 v[82:97], v[204:207], v[228:231], v[82:97]
	ds_read_b128 v[216:219], v136 offset:4096
	ds_read_b128 v[224:227], v136 offset:6144
	v_mfma_f32_32x32x16_bf16 v[66:81], v[204:207], v[236:239], v[66:81]
	v_mfma_f32_32x32x16_bf16 v[50:65], v[212:215], v[228:231], v[50:65]
	v_mfma_f32_32x32x16_bf16 v[34:49], v[212:215], v[236:239], v[34:49]
	v_mfma_f32_32x32x16_bf16 v[18:33], v[220:223], v[228:231], v[18:33]
	v_mfma_f32_32x32x16_bf16 v[2:17], v[220:223], v[236:239], v[2:17]
	s_waitcnt lgkmcnt(0)
	v_mfma_f32_32x32x16_bf16 v[114:129], v[166:169], v[232:235], v[114:129]
	v_mfma_f32_32x32x16_bf16 v[98:113], v[166:169], v[240:243], v[98:113]
	v_mfma_f32_32x32x16_bf16 v[82:97], v[208:211], v[232:235], v[82:97]
	v_mfma_f32_32x32x16_bf16 v[66:81], v[208:211], v[240:243], v[66:81]
	v_mfma_f32_32x32x16_bf16 v[50:65], v[216:219], v[232:235], v[50:65]
	v_mfma_f32_32x32x16_bf16 v[34:49], v[216:219], v[240:243], v[34:49]
	v_mfma_f32_32x32x16_bf16 v[18:33], v[224:227], v[232:235], v[18:33]
	v_mfma_f32_32x32x16_bf16 v[2:17], v[224:227], v[240:243], v[2:17]
	s_mov_b32 s14, 31
	s_lshl_b64 s[12:13], s[14:15], 13
	s_movk_i32 s7, 0x7800
	s_movk_i32 s72, 0x6000
	s_mov_b32 s73, 0xc000
	s_setprio 0
	s_movk_i32 s74, 0x104
	s_mov_b32 s75, 0x42ce8ed0
	s_mov_b32 s76, 0xbfb8aa3b
	s_mov_b32 s77, 0x1d730000
	v_mov_b32_e32 v0, v171
	s_barrier
	s_movk_i32 s0, 0x210
	s_waitcnt vmcnt(4)
	v_lshrrev_b32_e32 v130, 1, v0
	v_and_b32_e32 v130, 0xfffffc0, v130
	v_lshrrev_b32_e32 v131, 3, v0
	v_and_or_b32 v130, v131, 4, v130
	v_and_b32_e32 v0, 0x5f, v0
	v_mul_lo_u32 v130, v130, s0
	v_lshl_add_u32 v0, v0, 2, v130
	s_barrier
	ds_write2_b32 v0, v114, v98 offset1:32
	ds_write2_b32 v0, v115, v99 offset0:132 offset1:164
	v_add_u32_e32 v98, 0x400, v0
	ds_write2_b32 v98, v116, v100 offset0:8 offset1:40
	ds_write2_b32 v98, v117, v101 offset0:140 offset1:172
	v_add_u32_e32 v98, 0x1000, v0
	ds_write2_b32 v98, v118, v102 offset0:32 offset1:64
	ds_write2_b32 v98, v119, v103 offset0:164 offset1:196
	v_add_u32_e32 v98, 0x1400, v0
	ds_write2_b32 v98, v120, v104 offset0:40 offset1:72
	ds_write2_b32 v98, v121, v105 offset0:172 offset1:204
	v_add_u32_e32 v98, 0x2000, v0
	ds_write2_b32 v98, v122, v106 offset0:64 offset1:96
	ds_write2_b32 v98, v123, v107 offset0:196 offset1:228
	v_add_u32_e32 v98, 0x2400, v0
	ds_write2_b32 v98, v124, v108 offset0:72 offset1:104
	ds_write2_b32 v98, v125, v109 offset0:204 offset1:236
	v_add_u32_e32 v98, 0x3000, v0
	ds_write2_b32 v98, v126, v110 offset0:96 offset1:128
	v_add_u32_e32 v98, 0x3200, v0
	ds_write2_b32 v98, v127, v111 offset0:100 offset1:132
	v_add_u32_e32 v98, 0x3400, v0
	ds_write2_b32 v98, v128, v112 offset0:104 offset1:136
	v_add_u32_e32 v98, 0x3600, v0
	ds_write2_b32 v98, v129, v113 offset0:108 offset1:140
	v_add_u32_e32 v98, 0x4000, v0
	ds_write2_b32 v98, v82, v66 offset0:128 offset1:160
	v_add_u32_e32 v66, 0x4400, v0
	ds_write2_b32 v66, v83, v67 offset0:4 offset1:36
	ds_write2_b32 v66, v84, v68 offset0:136 offset1:168
	v_add_u32_e32 v66, 0x4800, v0
	ds_write2_b32 v66, v85, v69 offset0:12 offset1:44
	v_add_u32_e32 v66, 0x5000, v0
	ds_write2_b32 v66, v86, v70 offset0:160 offset1:192
	v_add_u32_e32 v66, 0x5400, v0
	ds_write2_b32 v66, v87, v71 offset0:36 offset1:68
	ds_write2_b32 v66, v88, v72 offset0:168 offset1:200
	v_add_u32_e32 v66, 0x5800, v0
	ds_write2_b32 v66, v89, v73 offset0:44 offset1:76
	v_add_u32_e32 v66, 0x6000, v0
	ds_write2_b32 v66, v90, v74 offset0:192 offset1:224
	v_add_u32_e32 v66, 0x6400, v0
	ds_write2_b32 v66, v91, v75 offset0:68 offset1:100
	ds_write2_b32 v66, v92, v76 offset0:200 offset1:232
	v_add_u32_e32 v66, 0x6800, v0
	ds_write2_b32 v66, v93, v77 offset0:76 offset1:108
	v_add_u32_e32 v66, 0x7200, v0
	ds_write2_b32 v66, v94, v78 offset0:96 offset1:128
	v_add_u32_e32 v66, 0x7400, v0
	s_lshr_b32 s14, s42, 2
	ds_write2_b32 v66, v95, v79 offset0:100 offset1:132
	v_add_u32_e32 v66, 0x7600, v0
	v_add_u32_e32 v0, 0x7800, v0
	v_mov_b32_e32 v105, v171
	s_cmp_lt_i32 s14, 14
	s_mov_b64 s[6:7], -1
	ds_write2_b32 v66, v96, v80 offset0:104 offset1:136
	ds_write2_b32 v0, v97, v81 offset0:108 offset1:140
	s_waitcnt lgkmcnt(0)
	s_barrier
	s_cbranch_scc1 .LBB0_439
	s_cmp_gt_i32 s14, 14
	s_cbranch_scc0 .LBB0_436
	s_mov_b64 s[6:7], 0

.Lg588_loop:
	s_setprio 0
	s_waitcnt lgkmcnt(0)
	v_mfma_f32_32x32x16_bf16 v[114:129], v[162:165], v[228:231], v[114:129]
	ds_read_b128 v[166:169], v136 offset:0
	ds_read_b128 v[232:235], v137 offset:0
	s_add_i32 s7, s7, 1
	s_add_i32 s14, s7, 2
	s_lshl_b64 s[12:13], s[14:15], 14
	s_add_u32 s12, s12, s74
	s_addc_u32 s13, s13, s75
	v_mfma_f32_32x32x16_bf16 v[98:113], v[162:165], v[236:239], v[98:113]
	ds_read_b128 v[240:243], v137 offset:2048
	ds_read_b128 v[208:211], v136 offset:2048
	v_mfma_f32_32x32x16_bf16 v[82:97], v[204:207], v[228:231], v[82:97]
	ds_read_b128 v[216:219], v136 offset:4096
	ds_read_b128 v[224:227], v136 offset:6144
	v_mfma_f32_32x32x16_bf16 v[66:81], v[204:207], v[236:239], v[66:81]
	v_mfma_f32_32x32x16_bf16 v[50:65], v[212:215], v[228:231], v[50:65]
	v_mfma_f32_32x32x16_bf16 v[34:49], v[212:215], v[236:239], v[34:49]
	v_mfma_f32_32x32x16_bf16 v[18:33], v[220:223], v[228:231], v[18:33]
	v_mfma_f32_32x32x16_bf16 v[2:17], v[220:223], v[236:239], v[2:17]
	s_waitcnt vmcnt(6) lgkmcnt(0)
	s_barrier
	s_setprio 1
	s_add_u32 m0, s11, s72
	s_mov_b32 s11, s73
	s_add_u32 s73, s11, 0x6000
	s_cmp_lt_u32 s73, 0x12000
	s_cselect_b32 s73, s73, 0
	v_mfma_f32_32x32x16_bf16 v[114:129], v[166:169], v[232:235], v[114:129]
	ds_read_b128 v[162:165], v138 offset:0
	ds_read_b128 v[228:231], v139 offset:0
	v_mfma_f32_32x32x16_bf16 v[98:113], v[166:169], v[240:243], v[98:113]
	ds_read_b128 v[236:239], v139 offset:2048
	ds_read_b128 v[204:207], v138 offset:2048
	v_add_u32_e32 v136, s11, v134
	v_add_u32_e32 v137, s11, v135
	v_mfma_f32_32x32x16_bf16 v[82:97], v[208:211], v[232:235], v[82:97]
	ds_read_b128 v[212:215], v138 offset:4096
	ds_read_b128 v[220:223], v138 offset:6144
	v_mfma_f32_32x32x16_bf16 v[66:81], v[208:211], v[240:243], v[66:81]
	global_load_lds_dwordx4 v140, s[12:13]
	s_add_u32 m0, m0, 0x1000
	s_add_u32 s12, s12, 0x1000
	s_addc_u32 s13, s13, 0
	v_add_u32_e32 v138, s73, v132
	v_add_u32_e32 v139, s73, v133
	v_mfma_f32_32x32x16_bf16 v[50:65], v[216:219], v[232:235], v[50:65]
	global_load_lds_dwordx4 v140, s[12:13]
	s_add_u32 m0, m0, 0x1000
	s_add_u32 s12, s12, 0x1000
	s_addc_u32 s13, s13, 0
	v_mfma_f32_32x32x16_bf16 v[34:49], v[216:219], v[240:243], v[34:49]
	global_load_lds_dwordx4 v140, s[12:13]
	s_add_u32 m0, m0, 0x1000
	s_add_u32 s12, s12, 0x1000
	s_addc_u32 s13, s13, 0
	v_mfma_f32_32x32x16_bf16 v[18:33], v[224:227], v[232:235], v[18:33]
	global_load_lds_dwordx4 v140, s[12:13]
	s_add_u32 m0, m0, 0x1000
	s_lshl_b64 s[12:13], s[14:15], 13
	s_add_u32 s12, s12, s76
	s_addc_u32 s13, s13, s77
	v_mfma_f32_32x32x16_bf16 v[2:17], v[224:227], v[240:243], v[2:17]
	global_load_lds_dwordx4 v140, s[12:13]
	s_add_u32 m0, m0, 0x1000
	s_add_u32 s12, s12, 0x1000
	s_addc_u32 s13, s13, 0
	s_nop 0
	global_load_lds_dwordx4 v140, s[12:13]
	s_cmp_lg_u32 s7, 125
	s_cbranch_scc1 .Lg588_loop
	s_setprio 0
	s_waitcnt lgkmcnt(0)
	v_mfma_f32_32x32x16_bf16 v[114:129], v[162:165], v[228:231], v[114:129]
	ds_read_b128 v[166:169], v136 offset:0
	ds_read_b128 v[232:235], v137 offset:0
	s_add_i32 s7, s7, 1
	v_mfma_f32_32x32x16_bf16 v[98:113], v[162:165], v[236:239], v[98:113]
	ds_read_b128 v[240:243], v137 offset:2048
	ds_read_b128 v[208:211], v136 offset:2048
	v_mfma_f32_32x32x16_bf16 v[82:97], v[204:207], v[228:231], v[82:97]
	ds_read_b128 v[216:219], v136 offset:4096
	ds_read_b128 v[224:227], v136 offset:6144
	v_mfma_f32_32x32x16_bf16 v[66:81], v[204:207], v[236:239], v[66:81]
	v_mfma_f32_32x32x16_bf16 v[50:65], v[212:215], v[228:231], v[50:65]
	v_mfma_f32_32x32x16_bf16 v[34:49], v[212:215], v[236:239], v[34:49]
	v_mfma_f32_32x32x16_bf16 v[18:33], v[220:223], v[228:231], v[18:33]
	v_mfma_f32_32x32x16_bf16 v[2:17], v[220:223], v[236:239], v[2:17]
	s_waitcnt vmcnt(6) lgkmcnt(0)
	s_barrier
	s_setprio 1
	s_mov_b32 s11, s73
	s_add_u32 s73, s11, 0x6000
	s_cmp_lt_u32 s73, 0x12000
	s_cselect_b32 s73, s73, 0
	v_mfma_f32_32x32x16_bf16 v[114:129], v[166:169], v[232:235], v[114:129]
	ds_read_b128 v[162:165], v138 offset:0
	ds_read_b128 v[228:231], v139 offset:0
	v_mfma_f32_32x32x16_bf16 v[98:113], v[166:169], v[240:243], v[98:113]
	ds_read_b128 v[236:239], v139 offset:2048
	ds_read_b128 v[204:207], v138 offset:2048
	v_add_u32_e32 v136, s11, v134
	v_add_u32_e32 v137, s11, v135
	v_mfma_f32_32x32x16_bf16 v[82:97], v[208:211], v[232:235], v[82:97]
	ds_read_b128 v[212:215], v138 offset:4096
	ds_read_b128 v[220:223], v138 offset:6144
	v_mfma_f32_32x32x16_bf16 v[66:81], v[208:211], v[240:243], v[66:81]
	v_add_u32_e32 v138, s73, v132
	v_add_u32_e32 v139, s73, v133
	v_mfma_f32_32x32x16_bf16 v[50:65], v[216:219], v[232:235], v[50:65]
	v_mfma_f32_32x32x16_bf16 v[34:49], v[216:219], v[240:243], v[34:49]
	v_mfma_f32_32x32x16_bf16 v[18:33], v[224:227], v[232:235], v[18:33]
	v_mfma_f32_32x32x16_bf16 v[2:17], v[224:227], v[240:243], v[2:17]
	s_setprio 0
	s_waitcnt lgkmcnt(0)
	v_mfma_f32_32x32x16_bf16 v[114:129], v[162:165], v[228:231], v[114:129]
	ds_read_b128 v[166:169], v136 offset:0
	ds_read_b128 v[232:235], v137 offset:0
	s_add_i32 s7, s7, 1
	v_mfma_f32_32x32x16_bf16 v[98:113], v[162:165], v[236:239], v[98:113]
	ds_read_b128 v[240:243], v137 offset:2048
	ds_read_b128 v[208:211], v136 offset:2048
	v_mfma_f32_32x32x16_bf16 v[82:97], v[204:207], v[228:231], v[82:97]
	ds_read_b128 v[216:219], v136 offset:4096
	ds_read_b128 v[224:227], v136 offset:6144
	v_mfma_f32_32x32x16_bf16 v[66:81], v[204:207], v[236:239], v[66:81]
	v_mfma_f32_32x32x16_bf16 v[50:65], v[212:215], v[228:231], v[50:65]
	v_mfma_f32_32x32x16_bf16 v[34:49], v[212:215], v[236:239], v[34:49]
	v_mfma_f32_32x32x16_bf16 v[18:33], v[220:223], v[228:231], v[18:33]
	v_mfma_f32_32x32x16_bf16 v[2:17], v[220:223], v[236:239], v[2:17]
	s_waitcnt vmcnt(0) lgkmcnt(0)
	s_barrier
	s_setprio 1
	s_mov_b32 s11, s73
	s_add_u32 s73, s11, 0x6000
	s_cmp_lt_u32 s73, 0x12000
	s_cselect_b32 s73, s73, 0
	v_mfma_f32_32x32x16_bf16 v[114:129], v[166:169], v[232:235], v[114:129]
	ds_read_b128 v[162:165], v138 offset:0
	ds_read_b128 v[228:231], v139 offset:0
	v_mfma_f32_32x32x16_bf16 v[98:113], v[166:169], v[240:243], v[98:113]
	ds_read_b128 v[236:239], v139 offset:2048
	ds_read_b128 v[204:207], v138 offset:2048
	v_add_u32_e32 v136, s11, v134
	v_add_u32_e32 v137, s11, v135
	v_mfma_f32_32x32x16_bf16 v[82:97], v[208:211], v[232:235], v[82:97]
	ds_read_b128 v[212:215], v138 offset:4096
	ds_read_b128 v[220:223], v138 offset:6144
	v_mfma_f32_32x32x16_bf16 v[66:81], v[208:211], v[240:243], v[66:81]
	v_add_u32_e32 v138, s73, v132
	v_add_u32_e32 v139, s73, v133
	v_mfma_f32_32x32x16_bf16 v[50:65], v[216:219], v[232:235], v[50:65]
	v_mfma_f32_32x32x16_bf16 v[34:49], v[216:219], v[240:243], v[34:49]
	v_mfma_f32_32x32x16_bf16 v[18:33], v[224:227], v[232:235], v[18:33]
	v_mfma_f32_32x32x16_bf16 v[2:17], v[224:227], v[240:243], v[2:17]
	s_setprio 0
	s_waitcnt lgkmcnt(0)
	v_mfma_f32_32x32x16_bf16 v[114:129], v[162:165], v[228:231], v[114:129]
	ds_read_b128 v[166:169], v136 offset:0
	ds_read_b128 v[232:235], v137 offset:0
	s_add_i32 s7, s7, 1
	v_mfma_f32_32x32x16_bf16 v[98:113], v[162:165], v[236:239], v[98:113]
	ds_read_b128 v[240:243], v137 offset:2048
	ds_read_b128 v[208:211], v136 offset:2048
	v_mfma_f32_32x32x16_bf16 v[82:97], v[204:207], v[228:231], v[82:97]
	ds_read_b128 v[216:219], v136 offset:4096
	ds_read_b128 v[224:227], v136 offset:6144
	v_mfma_f32_32x32x16_bf16 v[66:81], v[204:207], v[236:239], v[66:81]
	v_mfma_f32_32x32x16_bf16 v[50:65], v[212:215], v[228:231], v[50:65]
	v_mfma_f32_32x32x16_bf16 v[34:49], v[212:215], v[236:239], v[34:49]
	v_mfma_f32_32x32x16_bf16 v[18:33], v[220:223], v[228:231], v[18:33]
	v_mfma_f32_32x32x16_bf16 v[2:17], v[220:223], v[236:239], v[2:17]
	s_waitcnt lgkmcnt(0)
	v_mfma_f32_32x32x16_bf16 v[114:129], v[166:169], v[232:235], v[114:129]
	v_mfma_f32_32x32x16_bf16 v[98:113], v[166:169], v[240:243], v[98:113]
	v_mfma_f32_32x32x16_bf16 v[82:97], v[208:211], v[232:235], v[82:97]
	v_mfma_f32_32x32x16_bf16 v[66:81], v[208:211], v[240:243], v[66:81]
	v_mfma_f32_32x32x16_bf16 v[50:65], v[216:219], v[232:235], v[50:65]
	v_mfma_f32_32x32x16_bf16 v[34:49], v[216:219], v[240:243], v[34:49]
	v_mfma_f32_32x32x16_bf16 v[18:33], v[224:227], v[232:235], v[18:33]
	v_mfma_f32_32x32x16_bf16 v[2:17], v[224:227], v[240:243], v[2:17]
	s_mov_b32 s14, 127
	s_lshl_b64 s[12:13], s[14:15], 13
	s_movk_i32 s11, 0x7800
	s_movk_i32 s72, 0x6000
	s_mov_b32 s73, 0xc000
	s_setprio 0
	s_movk_i32 s74, 0x104
	s_mov_b32 s75, 0x42ce8ed0
	s_mov_b32 s76, 0xbfb8aa3b
	s_mov_b32 s77, 0x1d730000
	v_mov_b32_e32 v0, v171
	s_barrier
	s_movk_i32 s0, 0x210
	s_waitcnt vmcnt(4)
	v_lshrrev_b32_e32 v130, 1, v0
	v_and_b32_e32 v130, 0xfffffc0, v130
	v_lshrrev_b32_e32 v131, 3, v0
	v_and_or_b32 v130, v131, 4, v130
	v_and_b32_e32 v0, 0x5f, v0
	v_mul_lo_u32 v130, v130, s0
	v_lshl_add_u32 v0, v0, 2, v130
	s_barrier
	ds_write2_b32 v0, v114, v98 offset1:32
	ds_write2_b32 v0, v115, v99 offset0:132 offset1:164
	v_add_u32_e32 v98, 0x400, v0
	ds_write2_b32 v98, v116, v100 offset0:8 offset1:40
	ds_write2_b32 v98, v117, v101 offset0:140 offset1:172
	v_add_u32_e32 v98, 0x1000, v0
	ds_write2_b32 v98, v118, v102 offset0:32 offset1:64
	ds_write2_b32 v98, v119, v103 offset0:164 offset1:196
	v_add_u32_e32 v98, 0x1400, v0
	ds_write2_b32 v98, v120, v104 offset0:40 offset1:72
	ds_write2_b32 v98, v121, v105 offset0:172 offset1:204
	v_add_u32_e32 v98, 0x2000, v0
	ds_write2_b32 v98, v122, v106 offset0:64 offset1:96
	ds_write2_b32 v98, v123, v107 offset0:196 offset1:228
	v_add_u32_e32 v98, 0x2400, v0
	ds_write2_b32 v98, v124, v108 offset0:72 offset1:104
	ds_write2_b32 v98, v125, v109 offset0:204 offset1:236
	v_add_u32_e32 v98, 0x3000, v0
	ds_write2_b32 v98, v126, v110 offset0:96 offset1:128
	v_add_u32_e32 v98, 0x3200, v0
	ds_write2_b32 v98, v127, v111 offset0:100 offset1:132
	v_add_u32_e32 v98, 0x3400, v0
	ds_write2_b32 v98, v128, v112 offset0:104 offset1:136
	v_add_u32_e32 v98, 0x3600, v0
	ds_write2_b32 v98, v129, v113 offset0:108 offset1:140
	v_add_u32_e32 v98, 0x4000, v0
	ds_write2_b32 v98, v82, v66 offset0:128 offset1:160
	v_add_u32_e32 v66, 0x4400, v0
	ds_write2_b32 v66, v83, v67 offset0:4 offset1:36
	ds_write2_b32 v66, v84, v68 offset0:136 offset1:168
	v_add_u32_e32 v66, 0x4800, v0
	ds_write2_b32 v66, v85, v69 offset0:12 offset1:44
	v_add_u32_e32 v66, 0x5000, v0
	s_lshl_b32 s10, s10, 8
	ds_write2_b32 v66, v86, v70 offset0:160 offset1:192
	v_add_u32_e32 v66, 0x5400, v0
	s_lshl_b32 s11, s6, 7
	ds_write2_b32 v66, v87, v71 offset0:36 offset1:68
	ds_write2_b32 v66, v88, v72 offset0:168 offset1:200
	v_add_u32_e32 v66, 0x5800, v0
	s_add_i32 s6, s10, 0xffffe000
	ds_write2_b32 v66, v89, v73 offset0:44 offset1:76
	v_add_u32_e32 v66, 0x6000, v0
	s_lshr_b32 s6, s6, 12
	ds_write2_b32 v66, v90, v74 offset0:192 offset1:224
	v_add_u32_e32 v66, 0x6400, v0
	s_mulk_i32 s6, 0x1800
	ds_write2_b32 v66, v91, v75 offset0:68 offset1:100
	ds_write2_b32 v66, v92, v76 offset0:200 offset1:232
	v_add_u32_e32 v66, 0x6800, v0
	s_addk_i32 s6, 0x1800
	ds_write2_b32 v66, v93, v77 offset0:76 offset1:108
	v_add_u32_e32 v66, 0x7200, v0
	s_cmp_gt_u32 s9, 31
	ds_write2_b32 v66, v94, v78 offset0:96 offset1:128
	v_add_u32_e32 v66, 0x7400, v0
	s_cselect_b32 s14, s6, 0
	ds_write2_b32 v66, v95, v79 offset0:100 offset1:132
	v_add_u32_e32 v66, 0x7600, v0
	v_add_u32_e32 v0, 0x7800, v0
	v_mov_b32_e32 v84, v171
	s_lshl_b64 s[6:7], s[14:15], 2
	ds_write2_b32 v66, v96, v80 offset0:104 offset1:136
	ds_write2_b32 v0, v97, v81 offset0:108 offset1:140
	s_waitcnt lgkmcnt(0)
	s_barrier
	s_add_u32 s6, s61, s6
	v_lshlrev_b32_e32 v0, 3, v84
	v_and_b32_e32 v0, 0x78, v0
	s_addc_u32 s7, s53, s7
	v_or_b32_e32 v0, s11, v0
	s_add_u32 s6, s6, 0x1d645000
	s_addc_u32 s7, s7, 0
	v_lshlrev_b64 v[82:83], 2, v[0:1]
	v_lshl_add_u64 v[70:71], s[6:7], 0, v[82:83]
	v_lshl_add_u64 v[78:79], s[4:5], 0, v[82:83]
	global_load_dwordx4 v[66:69], v[70:71], off offset:16
	s_nop 0
	global_load_dwordx4 v[70:73], v[70:71], off
	s_nop 0
	global_load_dwordx4 v[74:77], v[78:79], off offset:16
	s_nop 0
	global_load_dwordx4 v[78:81], v[78:79], off
	v_ashrrev_i32_e32 v0, 4, v84
	v_mul_lo_u32 v85, v0, s0
	v_and_b32_e32 v84, 15, v84
	s_mov_b32 s9, 0
	v_lshl_add_u64 v[82:83], s[56:57], 0, v[82:83]
	v_lshl_add_u32 v84, v84, 5, v85
	v_lshlrev_b32_e32 v85, 1, v0
